# v49 + counted vmcnt waits in both out-proj epilogues: residual loads consumed group by group (vmcnt 12/12/20/20 and 12/14/24/26) instead of one vmcnt(0) after all 16 loads
# speedup vs baseline: 1.0159x; 1.0159x over previous
; __device__ __forceinline__ u32x4 pack8(f32x4 a, f32x4 b) { u32x4 w; w.x = cvt_pk_bf16(a[0], a[1]); w.y = cvt_pk_bf16(a[2], a[3]); w.z = cvt_pk_bf16(b[0], b[1]); w.w = cvt_pk_bf16(b[2], b[3]); return w; }
; __device__ __forceinline__ float sq4(f32x4 a) { return (a[0] * a[0] + a[1] * a[1]) + (a[2] * a[2] + a[3] * a[3]); }
;     __device__ __forceinline__ void load2(f32x4 (&xv)[2][2][2], const float* rb, int b) const {
; #pragma unroll
;         for (int mm = 0; mm < 2; ++mm) {
;             const float* xp = rb + (size_t)((b >> 1) * HALF + (2 * (b & 1) + mm) * 16) * DM;
; #pragma unroll
;             for (int bj = 0; bj < 2; ++bj) { xv[mm][bj][0] = *(const f32x4*)(xp + bj * HALF); xv[mm][bj][1] = *(const f32x4*)(xp + bj * HALF + 4); }
;         }
;     }
;     __device__ __forceinline__ void operator()(const f32x4 (&acc)[2][2][4][2], const Unit& u, int wr, int wc, int fr_, int fq_, int slot) const {
;         int fr = fr_, fq = fq_; asm volatile("" : "+v"(fr), "+v"(fq));
;         const int pn = u.pn, col0 = pn * BM + wc * 32 + 8 * fq;
;         const float* rb = ((u.pm * BM < MPROMPT) ? R0 : R1) + (size_t)(u.pm * BM + wr * 64 + fr) * DM + col0;
;         f32x4 xa[2][2][2], xb2[2][2][2];
;         load2(xa, rb, 0);
; #pragma unroll
;         for (int b = 0; b < 4; ++b) {
;             if (b + 1 < 4) { if (b & 1) load2(xa, rb, b + 1); else load2(xb2, rb, b + 1); }
;             const int ai = b >> 1;
; #pragma unroll
;             for (int mm = 0; mm < 2; ++mm) {
;                 const int m = 2 * (b & 1) + mm;
;                 const int row = u.pm * BM + ai * HALF + wr * 64 + m * 16 + fr;
;                 float* xp = X + (size_t)row * DM + col0; bf16_t* bp = XB + (size_t)row * DM + col0;
;                 float sq = 0.f;
; #pragma unroll
;                 for (int bj = 0; bj < 2; ++bj) {
;                     const f32x4 x0 = ((b & 1) ? xb2[mm][bj][0] : xa[mm][bj][0]) + acc[ai][bj][m][0], x1 = ((b & 1) ? xb2[mm][bj][1] : xa[mm][bj][1]) + acc[ai][bj][m][1];
;                     if (!dry) { *(f32x4*)(xp + bj * HALF) = x0; *(f32x4*)(xp + bj * HALF + 4) = x1;
;                     if (!lastl) *(u32x4*)(bp + bj * HALF) = pack8(x0, x1); }
;                     sq += sq4(x0) + sq4(x1);
;                 }
;                 if (!lastl) { sq = fq_sum(sq); if (fq == 0 && !dry) ss[(size_t)row * 16 + pn * 4 + wc] = sq; }
.LBB0_163:
	s_lshl_b32 s8, s44, 8
	v_mov_b32_e32 v122, v234
	v_mov_b32_e32 v126, v235
	s_or_b32 s8, s8, s23
	s_lshl_b32 s94, s44, 2
	v_lshl_add_u32 v210, v126, 3, s8
	s_lshl_b32 s8, s22, 8
	s_add_i32 s8, s8, s99
	v_add_u32_e32 v212, s8, v122
	v_ashrrev_i32_e32 v213, 31, v212
	v_lshlrev_b64 v[122:123], 12, v[212:213]
	v_lshl_add_u64 v[122:123], s[78:79], 0, v[122:123]
	v_ashrrev_i32_e32 v211, 31, v210
	v_lshl_add_u64 v[214:215], v[210:211], 2, v[122:123]
	s_mov_b64 s[8:9], 0x10000
	v_lshl_add_u64 v[122:123], v[214:215], 0, s[8:9]
	s_mov_b32 s8, 0x10000
	v_add_co_u32_e32 v124, vcc, s8, v214
	s_mov_b64 s[8:9], 0x10200
	s_nop 0
	v_addc_co_u32_e32 v125, vcc, 0, v215, vcc
	global_load_dwordx4 v[186:189], v[214:215], off offset:16
	global_load_dwordx4 v[190:193], v[214:215], off
	global_load_dwordx4 v[178:181], v[214:215], off offset:528
	global_load_dwordx4 v[182:185], v[214:215], off offset:512
	global_load_dwordx4 v[174:177], v[124:125], off
	global_load_dwordx4 v[170:173], v[122:123], off offset:16
	v_lshl_add_u64 v[122:123], v[214:215], 0, s[8:9]
	s_mov_b64 s[8:9], 0x20000
	global_load_dwordx4 v[166:169], v[124:125], off offset:512
	global_load_dwordx4 v[162:165], v[122:123], off offset:16
	v_lshl_add_u64 v[122:123], v[214:215], 0, s[8:9]
	s_mov_b32 s8, 0x20000
	v_add_co_u32_e32 v124, vcc, s8, v214
	s_mov_b64 s[8:9], 0x20200
	s_nop 0
	v_addc_co_u32_e32 v125, vcc, 0, v215, vcc
	global_load_dwordx4 v[158:161], v[124:125], off
	global_load_dwordx4 v[154:157], v[122:123], off offset:16
	v_lshl_add_u64 v[122:123], v[214:215], 0, s[8:9]
	s_mov_b64 s[8:9], 0x30000
	global_load_dwordx4 v[150:153], v[124:125], off offset:512
	global_load_dwordx4 v[146:149], v[122:123], off offset:16
	v_lshl_add_u64 v[122:123], v[214:215], 0, s[8:9]
	s_mov_b32 s8, 0x30000
	v_add_co_u32_e32 v124, vcc, s8, v214
	s_mov_b64 s[8:9], 0x30200
	s_nop 0
	v_addc_co_u32_e32 v125, vcc, 0, v215, vcc
	global_load_dwordx4 v[142:145], v[124:125], off
	global_load_dwordx4 v[138:141], v[122:123], off offset:16
	v_lshl_add_u64 v[122:123], v[214:215], 0, s[8:9]
	v_cmp_eq_u32_e64 s[42:43], 0, v126
	global_load_dwordx4 v[126:129], v[124:125], off offset:512
	s_nop 0
	global_load_dwordx4 v[122:125], v[122:123], off offset:16
	s_ashr_i32 s95, s94, 31
	s_mov_b64 s[92:93], -1
	s_andn2_b64 vcc, exec, s[84:85]
	s_waitcnt vmcnt(12)
	v_pk_add_f32 v[190:191], v[134:135], v[190:191]
	v_pk_add_f32 v[134:135], v[130:131], v[186:187]
	v_cndmask_b32_e64 v130, 0, 1, s[84:85]
	v_pk_add_f32 v[192:193], v[136:137], v[192:193]
	v_pk_add_f32 v[136:137], v[132:133], v[188:189]
	v_cmp_ne_u32_e64 s[44:45], 1, v130
	v_pk_add_f32 v[130:131], v[118:119], v[182:183]
	v_pk_add_f32 v[186:187], v[114:115], v[178:179]
	global_store_dwordx4 v[214:215], v[190:193], off
	global_store_dwordx4 v[214:215], v[134:137], off offset:16
	s_cbranch_vccnz .LBB0_167
	v_mul_f32_e32 v118, v191, v191
	v_mul_f32_e32 v119, v193, v193
	v_fmac_f32_e32 v118, v190, v190
	v_fmac_f32_e32 v119, v192, v192
	v_lshlrev_b64 v[114:115], 11, v[212:213]
	v_add_f32_e32 v118, v118, v119
	v_mul_f32_e32 v119, v135, v135
	v_lshl_add_u64 v[114:115], s[6:7], 0, v[114:115]
	v_cvt_pk_bf16_f32 v248, v190, v191
	v_cvt_pk_bf16_f32 v249, v192, v193
	v_cvt_pk_bf16_f32 v250, v134, v135
	v_fmac_f32_e32 v119, v134, v134
	v_mul_f32_e32 v134, v137, v137
	v_lshl_add_u64 v[114:115], v[210:211], 1, v[114:115]
	v_pk_add_f32 v[132:133], v[120:121], v[184:185]
	v_fmac_f32_e32 v134, v136, v136
	v_cvt_pk_bf16_f32 v251, v136, v137
	global_store_dwordx4 v[114:115], v[248:251], off
	v_pk_add_f32 v[188:189], v[116:117], v[180:181]
	global_store_dwordx4 v[214:215], v[130:133], off offset:512
	global_store_dwordx4 v[214:215], v[186:189], off offset:528
	v_add_f32_e32 v119, v119, v134
	v_cvt_pk_bf16_f32 v134, v130, v131
	v_cvt_pk_bf16_f32 v135, v132, v133
	v_cvt_pk_bf16_f32 v136, v186, v187
	v_cvt_pk_bf16_f32 v137, v188, v189
	global_store_dwordx4 v[114:115], v[134:137], off offset:256
	v_mul_f32_e32 v114, v131, v131
	v_mul_f32_e32 v115, v133, v133
	v_fmac_f32_e32 v114, v130, v130
	v_fmac_f32_e32 v115, v132, v132
	v_add_f32_e32 v118, v118, v119
	v_add_f32_e32 v114, v114, v115
	v_mul_f32_e32 v115, v187, v187
	v_mul_f32_e32 v119, v189, v189
	v_fmac_f32_e32 v115, v186, v186
	v_fmac_f32_e32 v119, v188, v188
	v_add_f32_e32 v115, v115, v119
	v_add_f32_e32 v114, v114, v115
	v_add_f32_e32 v114, v118, v114
	v_mov_b32_e32 v115, v114
	s_nop 1
	v_permlane16_swap_b32_e32 v114, v115
	v_add_f32_e32 v114, v114, v115
	v_mov_b32_e32 v115, v114
	s_nop 1
	v_permlane32_swap_b32_e32 v114, v115
	s_and_saveexec_b64 s[92:93], s[42:43]
	s_cbranch_execz .LBB0_166
	v_lshlrev_b64 v[118:119], 6, v[212:213]
	v_lshl_add_u64 v[118:119], s[96:97], 0, v[118:119]
	v_lshl_add_u64 v[118:119], s[94:95], 2, v[118:119]
	s_lshl_b32 s46, s98, 2
	v_lshl_add_u64 v[118:119], v[118:119], 0, s[46:47]
	v_add_f32_e32 v114, v114, v115
	global_store_dword v[118:119], v114, off

; __device__ __forceinline__ u32x4 pack8(f32x4 a, f32x4 b) { u32x4 w; w.x = cvt_pk_bf16(a[0], a[1]); w.y = cvt_pk_bf16(a[2], a[3]); w.z = cvt_pk_bf16(b[0], b[1]); w.w = cvt_pk_bf16(b[2], b[3]); return w; }
; __device__ __forceinline__ float sq4(f32x4 a) { return (a[0] * a[0] + a[1] * a[1]) + (a[2] * a[2] + a[3] * a[3]); }
;     __device__ __forceinline__ void operator()(const f32x4 (&acc)[2][2][4][2], const Unit& u, int wr, int wc, int fr_, int fq_, int slot) const {
;     ...
;             for (int mm = 0; mm < 2; ++mm) {
;                 const int m = 2 * (b & 1) + mm;
;                 const int row = u.pm * BM + ai * HALF + wr * 64 + m * 16 + fr;
;                 float* xp = X + (size_t)row * DM + col0; bf16_t* bp = XB + (size_t)row * DM + col0;
;                 float sq = 0.f;
; #pragma unroll
;                 for (int bj = 0; bj < 2; ++bj) {
;                     const f32x4 x0 = ((b & 1) ? xb2[mm][bj][0] : xa[mm][bj][0]) + acc[ai][bj][m][0], x1 = ((b & 1) ? xb2[mm][bj][1] : xa[mm][bj][1]) + acc[ai][bj][m][1];
;                     if (!dry) { *(f32x4*)(xp + bj * HALF) = x0; *(f32x4*)(xp + bj * HALF + 4) = x1;
;                     if (!lastl) *(u32x4*)(bp + bj * HALF) = pack8(x0, x1); }
;                     sq += sq4(x0) + sq4(x1);
;                 }
;                 if (!lastl) { sq = fq_sum(sq); if (fq == 0 && !dry) ss[(size_t)row * 16 + pn * 4 + wc] = sq; }
.LBB0_169:
	s_nop 0
	v_add_u32_e32 v132, 16, v212
	v_ashrrev_i32_e32 v133, 31, v132
	v_lshlrev_b64 v[114:115], 12, v[132:133]
	v_lshl_add_u64 v[114:115], s[78:79], 0, v[114:115]
	v_lshl_add_u64 v[130:131], v[210:211], 2, v[114:115]
	s_waitcnt vmcnt(12)
	v_pk_add_f32 v[116:117], v[110:111], v[176:177]
	v_pk_add_f32 v[114:115], v[108:109], v[174:175]
	v_pk_add_f32 v[120:121], v[106:107], v[172:173]
	v_pk_add_f32 v[118:119], v[104:105], v[170:171]
	s_mov_b64 s[92:93], -1
	s_and_b64 vcc, exec, s[44:45]
	v_pk_add_f32 v[108:109], v[100:101], v[166:167]
	v_pk_add_f32 v[104:105], v[96:97], v[162:163]
	v_readlane_b32 s13, v255, 49
	global_store_dwordx4 v[130:131], v[114:117], off
	global_store_dwordx4 v[130:131], v[118:121], off offset:16
	s_cbranch_vccnz .LBB0_173
	v_mul_f32_e32 v100, v115, v115
	v_mul_f32_e32 v101, v117, v117
	v_lshlrev_b64 v[96:97], 10, v[132:133]
	v_fmac_f32_e32 v100, v114, v114
	v_fmac_f32_e32 v101, v116, v116
	v_lshl_add_u64 v[96:97], v[96:97], 1, s[6:7]
	v_cvt_pk_bf16_f32 v134, v114, v115
	v_add_f32_e32 v100, v100, v101
	v_mul_f32_e32 v101, v119, v119
	v_mul_f32_e32 v114, v121, v121
	v_lshl_add_u64 v[96:97], v[210:211], 1, v[96:97]
	v_pk_add_f32 v[110:111], v[102:103], v[168:169]
	v_fmac_f32_e32 v101, v118, v118
	v_fmac_f32_e32 v114, v120, v120
	v_cvt_pk_bf16_f32 v135, v116, v117
	v_cvt_pk_bf16_f32 v136, v118, v119
	v_cvt_pk_bf16_f32 v137, v120, v121
	global_store_dwordx4 v[96:97], v[134:137], off
	v_pk_add_f32 v[106:107], v[98:99], v[164:165]
	global_store_dwordx4 v[130:131], v[108:111], off offset:512
	global_store_dwordx4 v[130:131], v[104:107], off offset:528
	v_add_f32_e32 v101, v101, v114
	v_cvt_pk_bf16_f32 v114, v108, v109
	v_cvt_pk_bf16_f32 v115, v110, v111
	v_cvt_pk_bf16_f32 v116, v104, v105
	v_cvt_pk_bf16_f32 v117, v106, v107
	global_store_dwordx4 v[96:97], v[114:117], off offset:256
	v_mul_f32_e32 v96, v109, v109
	v_mul_f32_e32 v97, v111, v111
	v_fmac_f32_e32 v96, v108, v108
	v_fmac_f32_e32 v97, v110, v110
	v_add_f32_e32 v100, v100, v101
	v_add_f32_e32 v96, v96, v97
	v_mul_f32_e32 v97, v105, v105
	v_mul_f32_e32 v101, v107, v107
	v_fmac_f32_e32 v97, v104, v104
	v_fmac_f32_e32 v101, v106, v106
	v_add_f32_e32 v97, v97, v101
	v_add_f32_e32 v96, v96, v97
	v_add_f32_e32 v96, v100, v96
	v_mov_b32_e32 v97, v96
	s_nop 1
	v_permlane16_swap_b32_e32 v96, v97
	v_add_f32_e32 v96, v96, v97
	v_mov_b32_e32 v97, v96
	s_nop 1
	v_permlane32_swap_b32_e32 v96, v97
	s_and_saveexec_b64 s[92:93], s[42:43]
	s_cbranch_execz .LBB0_172
	v_lshlrev_b64 v[100:101], 6, v[132:133]
	v_lshl_add_u64 v[100:101], s[96:97], 0, v[100:101]
	v_lshl_add_u64 v[100:101], s[94:95], 2, v[100:101]
	s_lshl_b32 s46, s98, 2
	v_lshl_add_u64 v[100:101], v[100:101], 0, s[46:47]
	v_add_f32_e32 v96, v96, v97
	global_store_dword v[100:101], v96, off

; __device__ __forceinline__ u32x4 pack8(f32x4 a, f32x4 b) { u32x4 w; w.x = cvt_pk_bf16(a[0], a[1]); w.y = cvt_pk_bf16(a[2], a[3]); w.z = cvt_pk_bf16(b[0], b[1]); w.w = cvt_pk_bf16(b[2], b[3]); return w; }
; __device__ __forceinline__ float sq4(f32x4 a) { return (a[0] * a[0] + a[1] * a[1]) + (a[2] * a[2] + a[3] * a[3]); }
;     __device__ __forceinline__ void operator()(const f32x4 (&acc)[2][2][4][2], const Unit& u, int wr, int wc, int fr_, int fq_, int slot) const {
;     ...
;         for (int b = 0; b < 4; ++b) {
;             if (b + 1 < 4) { if (b & 1) load2(xa, rb, b + 1); else load2(xb2, rb, b + 1); }
;             const int ai = b >> 1;
; #pragma unroll
;             for (int mm = 0; mm < 2; ++mm) {
;                 const int m = 2 * (b & 1) + mm;
;                 const int row = u.pm * BM + ai * HALF + wr * 64 + m * 16 + fr;
;                 float* xp = X + (size_t)row * DM + col0; bf16_t* bp = XB + (size_t)row * DM + col0;
;                 float sq = 0.f;
; #pragma unroll
;                 for (int bj = 0; bj < 2; ++bj) {
;                     const f32x4 x0 = ((b & 1) ? xb2[mm][bj][0] : xa[mm][bj][0]) + acc[ai][bj][m][0], x1 = ((b & 1) ? xb2[mm][bj][1] : xa[mm][bj][1]) + acc[ai][bj][m][1];
;                     if (!dry) { *(f32x4*)(xp + bj * HALF) = x0; *(f32x4*)(xp + bj * HALF + 4) = x1;
;                     if (!lastl) *(u32x4*)(bp + bj * HALF) = pack8(x0, x1); }
;                     sq += sq4(x0) + sq4(x1);
;                 }
;                 if (!lastl) { sq = fq_sum(sq); if (fq == 0 && !dry) ss[(size_t)row * 16 + pn * 4 + wc] = sq; }
.LBB0_175:
	s_mov_b64 s[8:9], 0x80000
	v_add_co_u32_e32 v98, vcc, 0x80000, v214
	v_lshl_add_u64 v[96:97], v[214:215], 0, s[8:9]
	s_nop 0
	v_addc_co_u32_e32 v99, vcc, 0, v215, vcc
	s_mov_b64 s[8:9], 0x80200
	global_load_dwordx4 v[134:137], v[98:99], off
	global_load_dwordx4 v[130:133], v[96:97], off offset:16
	v_lshl_add_u64 v[96:97], v[214:215], 0, s[8:9]
	s_mov_b32 s8, 0x90000
	global_load_dwordx4 v[118:121], v[98:99], off offset:512
	global_load_dwordx4 v[114:117], v[96:97], off offset:16
	v_add_co_u32_e32 v98, vcc, s8, v214
	v_lshl_add_u64 v[96:97], v[214:215], 0, s[4:5]
	s_nop 0
	v_addc_co_u32_e32 v99, vcc, 0, v215, vcc
	s_mov_b64 s[8:9], 0x90200
	global_load_dwordx4 v[108:111], v[98:99], off
	global_load_dwordx4 v[104:107], v[96:97], off offset:16
	v_lshl_add_u64 v[96:97], v[214:215], 0, s[8:9]
	global_load_dwordx4 v[100:103], v[98:99], off offset:512
	s_nop 0
	global_load_dwordx4 v[96:99], v[96:97], off offset:16
	v_add_u32_e32 v164, 32, v212
	v_ashrrev_i32_e32 v165, 31, v164
	v_lshlrev_b64 v[162:163], 12, v[164:165]
	v_lshl_add_u64 v[162:163], s[78:79], 0, v[162:163]
	v_lshl_add_u64 v[162:163], v[210:211], 2, v[162:163]
	s_waitcnt vmcnt(20)
	v_pk_add_f32 v[160:161], v[94:95], v[160:161]
	v_pk_add_f32 v[158:159], v[92:93], v[158:159]
	v_pk_add_f32 v[156:157], v[90:91], v[156:157]
	v_pk_add_f32 v[154:155], v[88:89], v[154:155]
	s_mov_b64 s[92:93], -1
	s_and_b64 vcc, exec, s[44:45]
	v_pk_add_f32 v[92:93], v[84:85], v[150:151]
	v_pk_add_f32 v[88:89], v[80:81], v[146:147]
	global_store_dwordx4 v[162:163], v[158:161], off
	global_store_dwordx4 v[162:163], v[154:157], off offset:16
	s_cbranch_vccnz .LBB0_179
	v_lshlrev_b64 v[80:81], 10, v[164:165]
	v_mul_f32_e32 v84, v159, v159
	v_mul_f32_e32 v85, v161, v161
	v_lshl_add_u64 v[80:81], v[80:81], 1, s[6:7]
	v_fmac_f32_e32 v84, v158, v158
	v_fmac_f32_e32 v85, v160, v160
	v_lshl_add_u64 v[80:81], v[210:211], 1, v[80:81]
	v_pk_add_f32 v[94:95], v[86:87], v[152:153]
	v_add_f32_e32 v84, v84, v85
	v_mul_f32_e32 v85, v155, v155
	v_mul_f32_e32 v146, v157, v157
	v_cvt_pk_bf16_f32 v166, v158, v159
	v_cvt_pk_bf16_f32 v167, v160, v161
	v_cvt_pk_bf16_f32 v168, v154, v155
	v_cvt_pk_bf16_f32 v169, v156, v157
	global_store_dwordx4 v[80:81], v[166:169], off
	v_pk_add_f32 v[90:91], v[82:83], v[148:149]
	global_store_dwordx4 v[162:163], v[92:95], off offset:512
	global_store_dwordx4 v[162:163], v[88:91], off offset:528
	v_fmac_f32_e32 v85, v154, v154
	v_fmac_f32_e32 v146, v156, v156
	v_cvt_pk_bf16_f32 v154, v92, v93
	v_cvt_pk_bf16_f32 v155, v94, v95
	v_cvt_pk_bf16_f32 v156, v88, v89
	v_cvt_pk_bf16_f32 v157, v90, v91
	global_store_dwordx4 v[80:81], v[154:157], off offset:256
	v_mul_f32_e32 v80, v93, v93
	v_mul_f32_e32 v81, v95, v95
	v_add_f32_e32 v85, v85, v146
	v_fmac_f32_e32 v80, v92, v92
	v_fmac_f32_e32 v81, v94, v94
	v_add_f32_e32 v84, v84, v85
	v_add_f32_e32 v80, v80, v81
	v_mul_f32_e32 v81, v89, v89
	v_mul_f32_e32 v85, v91, v91
	v_fmac_f32_e32 v81, v88, v88
	v_fmac_f32_e32 v85, v90, v90
	v_add_f32_e32 v81, v81, v85
	v_add_f32_e32 v80, v80, v81
	v_add_f32_e32 v80, v84, v80
	v_mov_b32_e32 v81, v80
	s_nop 1
	v_permlane16_swap_b32_e32 v80, v81
	v_add_f32_e32 v80, v80, v81
	v_mov_b32_e32 v81, v80
	s_nop 1
	v_permlane32_swap_b32_e32 v80, v81
	s_and_saveexec_b64 s[92:93], s[42:43]
	s_cbranch_execz .LBB0_178
	v_lshlrev_b64 v[84:85], 6, v[164:165]
	v_lshl_add_u64 v[84:85], s[96:97], 0, v[84:85]
	v_lshl_add_u64 v[84:85], s[94:95], 2, v[84:85]
	s_lshl_b32 s46, s98, 2
	v_lshl_add_u64 v[84:85], v[84:85], 0, s[46:47]
	v_add_f32_e32 v80, v80, v81
	global_store_dword v[84:85], v80, off

; __device__ __forceinline__ u32x4 pack8(f32x4 a, f32x4 b) { u32x4 w; w.x = cvt_pk_bf16(a[0], a[1]); w.y = cvt_pk_bf16(a[2], a[3]); w.z = cvt_pk_bf16(b[0], b[1]); w.w = cvt_pk_bf16(b[2], b[3]); return w; }
; __device__ __forceinline__ float sq4(f32x4 a) { return (a[0] * a[0] + a[1] * a[1]) + (a[2] * a[2] + a[3] * a[3]); }
;     __device__ __forceinline__ void operator()(const f32x4 (&acc)[2][2][4][2], const Unit& u, int wr, int wc, int fr_, int fq_, int slot) const {
;     ...
;             for (int mm = 0; mm < 2; ++mm) {
;                 const int m = 2 * (b & 1) + mm;
;                 const int row = u.pm * BM + ai * HALF + wr * 64 + m * 16 + fr;
;                 float* xp = X + (size_t)row * DM + col0; bf16_t* bp = XB + (size_t)row * DM + col0;
;                 float sq = 0.f;
; #pragma unroll
;                 for (int bj = 0; bj < 2; ++bj) {
;                     const f32x4 x0 = ((b & 1) ? xb2[mm][bj][0] : xa[mm][bj][0]) + acc[ai][bj][m][0], x1 = ((b & 1) ? xb2[mm][bj][1] : xa[mm][bj][1]) + acc[ai][bj][m][1];
;                     if (!dry) { *(f32x4*)(xp + bj * HALF) = x0; *(f32x4*)(xp + bj * HALF + 4) = x1;
;                     if (!lastl) *(u32x4*)(bp + bj * HALF) = pack8(x0, x1); }
;                     sq += sq4(x0) + sq4(x1);
;                 }
;                 if (!lastl) { sq = fq_sum(sq); if (fq == 0 && !dry) ss[(size_t)row * 16 + pn * 4 + wc] = sq; }
.LBB0_181:
	s_nop 1
	v_add_u32_e32 v90, 48, v212
	v_ashrrev_i32_e32 v91, 31, v90
	v_lshlrev_b64 v[80:81], 12, v[90:91]
	v_lshl_add_u64 v[80:81], s[78:79], 0, v[80:81]
	v_lshl_add_u64 v[88:89], v[210:211], 2, v[80:81]
	s_waitcnt vmcnt(20)
	v_pk_add_f32 v[82:83], v[78:79], v[144:145]
	v_pk_add_f32 v[80:81], v[76:77], v[142:143]
	v_pk_add_f32 v[86:87], v[74:75], v[140:141]
	v_pk_add_f32 v[84:85], v[72:73], v[138:139]
	s_mov_b64 s[92:93], -1
	s_and_b64 vcc, exec, s[44:45]
	v_pk_add_f32 v[76:77], v[68:69], v[126:127]
	v_pk_add_f32 v[72:73], v[64:65], v[122:123]
	global_store_dwordx4 v[88:89], v[80:83], off
	global_store_dwordx4 v[88:89], v[84:87], off offset:16
	s_cbranch_vccnz .LBB0_185
	v_mul_f32_e32 v68, v81, v81
	v_mul_f32_e32 v69, v83, v83
	v_lshlrev_b64 v[64:65], 10, v[90:91]
	v_fmac_f32_e32 v68, v80, v80
	v_fmac_f32_e32 v69, v82, v82
	v_lshl_add_u64 v[64:65], v[64:65], 1, s[6:7]
	v_cvt_pk_bf16_f32 v92, v80, v81
	v_add_f32_e32 v68, v68, v69
	v_mul_f32_e32 v69, v85, v85
	v_mul_f32_e32 v80, v87, v87
	v_lshl_add_u64 v[64:65], v[210:211], 1, v[64:65]
	v_pk_add_f32 v[78:79], v[70:71], v[128:129]
	v_fmac_f32_e32 v69, v84, v84
	v_fmac_f32_e32 v80, v86, v86
	v_cvt_pk_bf16_f32 v93, v82, v83
	v_cvt_pk_bf16_f32 v94, v84, v85
	v_cvt_pk_bf16_f32 v95, v86, v87
	global_store_dwordx4 v[64:65], v[92:95], off
	v_pk_add_f32 v[74:75], v[66:67], v[124:125]
	global_store_dwordx4 v[88:89], v[76:79], off offset:512
	global_store_dwordx4 v[88:89], v[72:75], off offset:528
	v_add_f32_e32 v69, v69, v80
	v_cvt_pk_bf16_f32 v80, v76, v77
	v_cvt_pk_bf16_f32 v81, v78, v79
	v_cvt_pk_bf16_f32 v82, v72, v73
	v_cvt_pk_bf16_f32 v83, v74, v75
	global_store_dwordx4 v[64:65], v[80:83], off offset:256
	v_mul_f32_e32 v64, v77, v77
	v_mul_f32_e32 v65, v79, v79
	v_fmac_f32_e32 v64, v76, v76
	v_fmac_f32_e32 v65, v78, v78
	v_add_f32_e32 v68, v68, v69
	v_add_f32_e32 v64, v64, v65
	v_mul_f32_e32 v65, v73, v73
	v_mul_f32_e32 v69, v75, v75
	v_fmac_f32_e32 v65, v72, v72
	v_fmac_f32_e32 v69, v74, v74
	v_add_f32_e32 v65, v65, v69
	v_add_f32_e32 v64, v64, v65
	v_add_f32_e32 v64, v68, v64
	v_mov_b32_e32 v65, v64
	s_nop 1
	v_permlane16_swap_b32_e32 v64, v65
	v_add_f32_e32 v64, v64, v65
	v_mov_b32_e32 v65, v64
	s_nop 1
	v_permlane32_swap_b32_e32 v64, v65
	s_and_saveexec_b64 s[92:93], s[42:43]
	s_cbranch_execz .LBB0_184
	v_lshlrev_b64 v[68:69], 6, v[90:91]
	v_lshl_add_u64 v[68:69], s[96:97], 0, v[68:69]
	v_lshl_add_u64 v[68:69], s[94:95], 2, v[68:69]
	s_lshl_b32 s46, s98, 2
	v_lshl_add_u64 v[68:69], v[68:69], 0, s[46:47]
	v_add_f32_e32 v64, v64, v65
	global_store_dword v[68:69], v64, off

; __device__ __forceinline__ u32x4 pack8(f32x4 a, f32x4 b) { u32x4 w; w.x = cvt_pk_bf16(a[0], a[1]); w.y = cvt_pk_bf16(a[2], a[3]); w.z = cvt_pk_bf16(b[0], b[1]); w.w = cvt_pk_bf16(b[2], b[3]); return w; }
; __device__ __forceinline__ float sq4(f32x4 a) { return (a[0] * a[0] + a[1] * a[1]) + (a[2] * a[2] + a[3] * a[3]); }
;     __device__ __forceinline__ void load2(f32x4 (&xv)[2][2][2], const float* rb, int b) const {
; #pragma unroll
;         for (int mm = 0; mm < 2; ++mm) {
;             const float* xp = rb + (size_t)((b >> 1) * HALF + (2 * (b & 1) + mm) * 16) * DM;
; #pragma unroll
;             for (int bj = 0; bj < 2; ++bj) { xv[mm][bj][0] = *(const f32x4*)(xp + bj * HALF); xv[mm][bj][1] = *(const f32x4*)(xp + bj * HALF + 4); }
;         }
;     }
;     __device__ __forceinline__ void operator()(const f32x4 (&acc)[2][2][4][2], const Unit& u, int wr, int wc, int fr_, int fq_, int slot) const {
;         int fr = fr_, fq = fq_; asm volatile("" : "+v"(fr), "+v"(fq));
;         const int pn = u.pn, col0 = pn * BM + wc * 32 + 8 * fq;
;         const float* rb = ((u.pm * BM < MPROMPT) ? R0 : R1) + (size_t)(u.pm * BM + wr * 64 + fr) * DM + col0;
;         f32x4 xa[2][2][2], xb2[2][2][2];
;         load2(xa, rb, 0);
; #pragma unroll
;         for (int b = 0; b < 4; ++b) {
;             if (b + 1 < 4) { if (b & 1) load2(xa, rb, b + 1); else load2(xb2, rb, b + 1); }
;             const int ai = b >> 1;
; #pragma unroll
;             for (int mm = 0; mm < 2; ++mm) {
;                 const int m = 2 * (b & 1) + mm;
;                 const int row = u.pm * BM + ai * HALF + wr * 64 + m * 16 + fr;
;                 float* xp = X + (size_t)row * DM + col0; bf16_t* bp = XB + (size_t)row * DM + col0;
;                 float sq = 0.f;
; #pragma unroll
;                 for (int bj = 0; bj < 2; ++bj) {
;                     const f32x4 x0 = ((b & 1) ? xb2[mm][bj][0] : xa[mm][bj][0]) + acc[ai][bj][m][0], x1 = ((b & 1) ? xb2[mm][bj][1] : xa[mm][bj][1]) + acc[ai][bj][m][1];
;                     if (!dry) { *(f32x4*)(xp + bj * HALF) = x0; *(f32x4*)(xp + bj * HALF + 4) = x1;
;                     if (!lastl) *(u32x4*)(bp + bj * HALF) = pack8(x0, x1); }
;                     sq += sq4(x0) + sq4(x1);
;                 }
;                 if (!lastl) { sq = fq_sum(sq); if (fq == 0 && !dry) ss[(size_t)row * 16 + pn * 4 + wc] = sq; }
.LBB0_233:
	s_lshl_b32 s8, s86, 8
	s_or_b32 s8, s8, s93
	v_mov_b32_e32 v246, v235
	v_mov_b32_e32 v130, v234
	s_cmpk_lt_i32 s37, 0x80
	s_cselect_b32 s9, s57, s95
	v_lshl_add_u32 v202, v246, 3, s8
	s_cselect_b32 s8, s94, s98
	s_lshl_b32 s13, s37, 8
	s_add_i32 s13, s13, s92
	v_add_u32_e32 v204, s13, v130
	v_ashrrev_i32_e32 v205, 31, v204
	v_lshlrev_b64 v[208:209], 12, v[204:205]
	v_ashrrev_i32_e32 v203, 31, v202
	v_lshl_add_u64 v[130:131], s[8:9], 0, v[208:209]
	v_lshlrev_b64 v[228:229], 2, v[202:203]
	v_lshl_add_u64 v[206:207], v[130:131], 0, v[228:229]
	s_mov_b64 s[8:9], 0x10000
	v_lshl_add_u64 v[130:131], v[206:207], 0, s[8:9]
	s_mov_b32 s8, 0x10000
	v_add_co_u32_e32 v132, vcc, s8, v206
	s_mov_b64 s[8:9], 0x10200
	v_lshl_add_u64 v[134:135], v[206:207], 0, s[8:9]
	s_mov_b64 s[8:9], 0x20000
	v_addc_co_u32_e32 v133, vcc, 0, v207, vcc
	v_lshl_add_u64 v[136:137], v[206:207], 0, s[8:9]
	s_mov_b32 s8, 0x20000
	v_add_co_u32_e32 v138, vcc, s8, v206
	s_mov_b64 s[8:9], 0x20200
	global_load_dwordx4 v[212:215], v[206:207], off
	global_load_dwordx4 v[236:239], v[206:207], off offset:16
	global_load_dwordx4 v[182:185], v[206:207], off offset:512
	global_load_dwordx4 v[178:181], v[206:207], off offset:528
	v_lshl_add_u64 v[140:141], v[206:207], 0, s[8:9]
	s_mov_b64 s[8:9], 0x30000
	v_addc_co_u32_e32 v139, vcc, 0, v207, vcc
	v_lshl_add_u64 v[240:241], v[206:207], 0, s[8:9]
	s_mov_b32 s8, 0x30000
	v_add_co_u32_e32 v242, vcc, s8, v206
	s_mov_b64 s[8:9], 0x30200
	s_nop 0
	v_addc_co_u32_e32 v243, vcc, 0, v207, vcc
	v_lshl_add_u64 v[244:245], v[206:207], 0, s[8:9]
	global_load_dwordx4 v[174:177], v[132:133], off
	global_load_dwordx4 v[170:173], v[130:131], off offset:16
	global_load_dwordx4 v[166:169], v[132:133], off offset:512
	global_load_dwordx4 v[162:165], v[134:135], off offset:16
	global_load_dwordx4 v[158:161], v[138:139], off
	global_load_dwordx4 v[154:157], v[136:137], off offset:16
	global_load_dwordx4 v[150:153], v[138:139], off offset:512
	global_load_dwordx4 v[146:149], v[140:141], off offset:16
	global_load_dwordx4 v[142:145], v[242:243], off
	s_nop 0
	global_load_dwordx4 v[138:141], v[240:241], off offset:16
	global_load_dwordx4 v[130:133], v[242:243], off offset:512
	global_load_dwordx4 v[134:137], v[244:245], off offset:16
	v_lshl_add_u64 v[208:209], s[78:79], 0, v[208:209]
	v_lshlrev_b64 v[240:241], 11, v[204:205]
	v_lshl_add_u64 v[228:229], v[208:209], 0, v[228:229]
	v_lshl_add_u64 v[240:241], s[6:7], 0, v[240:241]
	v_lshl_add_u64 v[208:209], v[202:203], 1, v[240:241]
	s_lshl_b32 s86, s86, 2
	v_cmp_eq_u32_e64 s[40:41], 0, v246
	s_ashr_i32 s87, s86, 31
	s_waitcnt vmcnt(12)
	v_pk_add_f32 v[128:129], v[128:129], v[214:215]
	v_pk_add_f32 v[126:127], v[126:127], v[212:213]
	v_pk_add_f32 v[124:125], v[124:125], v[238:239]
	v_pk_add_f32 v[122:123], v[122:123], v[236:237]
	v_pk_add_f32 v[118:119], v[118:119], v[182:183]
	v_pk_add_f32 v[114:115], v[114:115], v[178:179]
	global_store_dwordx4 v[228:229], v[126:129], off
	global_store_dwordx4 v[228:229], v[122:125], off offset:16
	v_cvt_pk_bf16_f32 v178, v126, v127
	v_cvt_pk_bf16_f32 v179, v128, v129
	v_mul_f32_e32 v182, v123, v123
	v_mul_f32_e32 v127, v127, v127
	v_mul_f32_e32 v129, v129, v129
	v_mul_f32_e32 v183, v125, v125
	v_pk_add_f32 v[120:121], v[120:121], v[184:185]
	v_mul_f32_e32 v184, v119, v119
	v_fmac_f32_e32 v127, v126, v126
	v_fmac_f32_e32 v129, v128, v128
	v_fmac_f32_e32 v182, v122, v122
	v_fmac_f32_e32 v183, v124, v124
	v_pk_add_f32 v[116:117], v[116:117], v[180:181]
	v_cvt_pk_bf16_f32 v180, v122, v123
	v_cvt_pk_bf16_f32 v181, v124, v125
	global_store_dwordx4 v[208:209], v[178:181], off
	global_store_dwordx4 v[228:229], v[118:121], off offset:512
	global_store_dwordx4 v[228:229], v[114:117], off offset:528
	v_cvt_pk_bf16_f32 v122, v118, v119
	v_cvt_pk_bf16_f32 v123, v120, v121
	v_cvt_pk_bf16_f32 v124, v114, v115
	v_fmac_f32_e32 v184, v118, v118
	v_add_f32_e32 v118, v127, v129
	v_add_f32_e32 v119, v182, v183
	v_mul_f32_e32 v115, v115, v115
	v_add_f32_e32 v118, v118, v119
	v_mul_f32_e32 v119, v121, v121
	v_fmac_f32_e32 v115, v114, v114
	v_mul_f32_e32 v114, v117, v117
	v_fmac_f32_e32 v119, v120, v120
	v_fmac_f32_e32 v114, v116, v116
	v_add_f32_e32 v119, v184, v119
	v_add_f32_e32 v114, v115, v114
	v_add_f32_e32 v114, v119, v114
	v_add_f32_e32 v114, v118, v114
	v_mov_b32_e32 v115, v114
	s_nop 1
	v_permlane16_swap_b32_e32 v114, v115
	v_add_f32_e32 v114, v114, v115
	v_mov_b32_e32 v115, v114
	s_nop 1
	v_permlane32_swap_b32_e32 v114, v115
	v_cvt_pk_bf16_f32 v125, v116, v117
	global_store_dwordx4 v[208:209], v[122:125], off offset:256
	s_and_saveexec_b64 s[88:89], s[40:41]
	v_readlane_b32 s96, v255, 45
	v_readlane_b32 s97, v255, 46
	s_cbranch_execz .LBB0_235
	v_lshlrev_b64 v[116:117], 6, v[204:205]
	v_lshl_add_u64 v[116:117], s[96:97], 0, v[116:117]
	v_lshl_add_u64 v[116:117], s[86:87], 2, v[116:117]
	s_lshl_b32 s46, s35, 2
	v_lshl_add_u64 v[116:117], v[116:117], 0, s[46:47]
	v_add_f32_e32 v114, v114, v115
	global_store_dword v[116:117], v114, off
; __device__ __forceinline__ u32x4 pack8(f32x4 a, f32x4 b) { u32x4 w; w.x = cvt_pk_bf16(a[0], a[1]); w.y = cvt_pk_bf16(a[2], a[3]); w.z = cvt_pk_bf16(b[0], b[1]); w.w = cvt_pk_bf16(b[2], b[3]); return w; }
; __device__ __forceinline__ float sq4(f32x4 a) { return (a[0] * a[0] + a[1] * a[1]) + (a[2] * a[2] + a[3] * a[3]); }
;     __device__ __forceinline__ void operator()(const f32x4 (&acc)[2][2][4][2], const Unit& u, int wr, int wc, int fr_, int fq_, int slot) const {
;     ...
;             for (int mm = 0; mm < 2; ++mm) {
;                 const int m = 2 * (b & 1) + mm;
;                 const int row = u.pm * BM + ai * HALF + wr * 64 + m * 16 + fr;
;                 float* xp = X + (size_t)row * DM + col0; bf16_t* bp = XB + (size_t)row * DM + col0;
;                 float sq = 0.f;
; #pragma unroll
;                 for (int bj = 0; bj < 2; ++bj) {
;                     const f32x4 x0 = ((b & 1) ? xb2[mm][bj][0] : xa[mm][bj][0]) + acc[ai][bj][m][0], x1 = ((b & 1) ? xb2[mm][bj][1] : xa[mm][bj][1]) + acc[ai][bj][m][1];
;                     if (!dry) { *(f32x4*)(xp + bj * HALF) = x0; *(f32x4*)(xp + bj * HALF + 4) = x1;
;                     if (!lastl) *(u32x4*)(bp + bj * HALF) = pack8(x0, x1); }
;                     sq += sq4(x0) + sq4(x1);
;                 }
;                 if (!lastl) { sq = fq_sum(sq); if (fq == 0 && !dry) ss[(size_t)row * 16 + pn * 4 + wc] = sq; }
.LBB0_235:
	s_or_b64 exec, exec, s[88:89]
	v_add_u32_e32 v114, 16, v204
	v_ashrrev_i32_e32 v115, 31, v114
	v_lshlrev_b64 v[116:117], 12, v[114:115]
	v_lshl_add_u64 v[116:117], s[78:79], 0, v[116:117]
	v_lshl_add_u64 v[120:121], v[202:203], 2, v[116:117]
	v_lshlrev_b64 v[116:117], 11, v[114:115]
	v_lshl_add_u64 v[116:117], s[6:7], 0, v[116:117]
	s_waitcnt vmcnt(14)
	v_pk_add_f32 v[110:111], v[110:111], v[176:177]
	v_pk_add_f32 v[108:109], v[108:109], v[174:175]
	v_pk_add_f32 v[104:105], v[104:105], v[170:171]
	v_lshl_add_u64 v[122:123], v[202:203], 1, v[116:117]
	v_pk_add_f32 v[106:107], v[106:107], v[172:173]
	global_store_dwordx4 v[120:121], v[108:111], off
	global_store_dwordx4 v[120:121], v[104:107], off offset:16
	v_cvt_pk_bf16_f32 v116, v108, v109
	v_cvt_pk_bf16_f32 v117, v110, v111
	v_cvt_pk_bf16_f32 v118, v104, v105
	v_pk_add_f32 v[102:103], v[102:103], v[168:169]
	v_mul_f32_e32 v109, v109, v109
	v_mul_f32_e32 v105, v105, v105
	v_fmac_f32_e32 v109, v108, v108
	v_mul_f32_e32 v108, v111, v111
	v_fmac_f32_e32 v105, v104, v104
	v_mul_f32_e32 v104, v107, v107
	v_fmac_f32_e32 v108, v110, v110
	v_fmac_f32_e32 v104, v106, v106
	v_add_f32_e32 v108, v109, v108
	v_add_f32_e32 v104, v105, v104
	v_pk_add_f32 v[100:101], v[100:101], v[166:167]
	v_pk_add_f32 v[96:97], v[96:97], v[162:163]
	v_cvt_pk_bf16_f32 v119, v106, v107
	global_store_dwordx4 v[122:123], v[116:119], off
	v_add_f32_e32 v108, v108, v104
	v_pk_add_f32 v[98:99], v[98:99], v[164:165]
	global_store_dwordx4 v[120:121], v[100:103], off offset:512
	global_store_dwordx4 v[120:121], v[96:99], off offset:528
	v_cvt_pk_bf16_f32 v104, v100, v101
	v_cvt_pk_bf16_f32 v105, v102, v103
	v_cvt_pk_bf16_f32 v106, v96, v97
	v_cvt_pk_bf16_f32 v107, v98, v99
	s_nop 0
	v_mul_f32_e32 v101, v101, v101
	v_mul_f32_e32 v97, v97, v97
	v_fmac_f32_e32 v101, v100, v100
	v_mul_f32_e32 v100, v103, v103
	v_fmac_f32_e32 v97, v96, v96
	v_mul_f32_e32 v96, v99, v99
	v_fmac_f32_e32 v100, v102, v102
	v_fmac_f32_e32 v96, v98, v98
	v_add_f32_e32 v100, v101, v100
	v_add_f32_e32 v96, v97, v96
	v_add_f32_e32 v96, v100, v96
	v_add_f32_e32 v96, v108, v96
	v_mov_b32_e32 v97, v96
	s_nop 1
	v_permlane16_swap_b32_e32 v96, v97
	v_add_f32_e32 v96, v96, v97
	v_mov_b32_e32 v97, v96
	s_nop 1
	v_permlane32_swap_b32_e32 v96, v97
	global_store_dwordx4 v[122:123], v[104:107], off offset:256
	s_and_saveexec_b64 s[88:89], s[40:41]
	s_cbranch_execz .LBB0_237
	v_lshlrev_b64 v[98:99], 6, v[114:115]
	v_lshl_add_u64 v[98:99], s[96:97], 0, v[98:99]
	v_lshl_add_u64 v[98:99], s[86:87], 2, v[98:99]
	s_lshl_b32 s46, s35, 2
	v_lshl_add_u64 v[98:99], v[98:99], 0, s[46:47]
	v_add_f32_e32 v96, v96, v97
	global_store_dword v[98:99], v96, off
; __device__ __forceinline__ u32x4 pack8(f32x4 a, f32x4 b) { u32x4 w; w.x = cvt_pk_bf16(a[0], a[1]); w.y = cvt_pk_bf16(a[2], a[3]); w.z = cvt_pk_bf16(b[0], b[1]); w.w = cvt_pk_bf16(b[2], b[3]); return w; }
; __device__ __forceinline__ float sq4(f32x4 a) { return (a[0] * a[0] + a[1] * a[1]) + (a[2] * a[2] + a[3] * a[3]); }
;     __device__ __forceinline__ void load2(f32x4 (&xv)[2][2][2], const float* rb, int b) const {
; #pragma unroll
;         for (int mm = 0; mm < 2; ++mm) {
;             const float* xp = rb + (size_t)((b >> 1) * HALF + (2 * (b & 1) + mm) * 16) * DM;
; #pragma unroll
;             for (int bj = 0; bj < 2; ++bj) { xv[mm][bj][0] = *(const f32x4*)(xp + bj * HALF); xv[mm][bj][1] = *(const f32x4*)(xp + bj * HALF + 4); }
;         }
;     }
;     __device__ __forceinline__ void operator()(const f32x4 (&acc)[2][2][4][2], const Unit& u, int wr, int wc, int fr_, int fq_, int slot) const {
;         int fr = fr_, fq = fq_; asm volatile("" : "+v"(fr), "+v"(fq));
;         const int pn = u.pn, col0 = pn * BM + wc * 32 + 8 * fq;
;         const float* rb = ((u.pm * BM < MPROMPT) ? R0 : R1) + (size_t)(u.pm * BM + wr * 64 + fr) * DM + col0;
;         f32x4 xa[2][2][2], xb2[2][2][2];
;         load2(xa, rb, 0);
; #pragma unroll
;         for (int b = 0; b < 4; ++b) {
;             if (b + 1 < 4) { if (b & 1) load2(xa, rb, b + 1); else load2(xb2, rb, b + 1); }
;             const int ai = b >> 1;
; #pragma unroll
;             for (int mm = 0; mm < 2; ++mm) {
;                 const int m = 2 * (b & 1) + mm;
;                 const int row = u.pm * BM + ai * HALF + wr * 64 + m * 16 + fr;
;                 float* xp = X + (size_t)row * DM + col0; bf16_t* bp = XB + (size_t)row * DM + col0;
;                 float sq = 0.f;
; #pragma unroll
;                 for (int bj = 0; bj < 2; ++bj) {
;                     const f32x4 x0 = ((b & 1) ? xb2[mm][bj][0] : xa[mm][bj][0]) + acc[ai][bj][m][0], x1 = ((b & 1) ? xb2[mm][bj][1] : xa[mm][bj][1]) + acc[ai][bj][m][1];
;                     if (!dry) { *(f32x4*)(xp + bj * HALF) = x0; *(f32x4*)(xp + bj * HALF + 4) = x1;
;                     if (!lastl) *(u32x4*)(bp + bj * HALF) = pack8(x0, x1); }
;                     sq += sq4(x0) + sq4(x1);
;                 }
;                 if (!lastl) { sq = fq_sum(sq); if (fq == 0 && !dry) ss[(size_t)row * 16 + pn * 4 + wc] = sq; }
.LBB0_237:
	s_or_b64 exec, exec, s[88:89]
	s_mov_b64 s[8:9], 0x80000
	v_add_co_u32_e32 v98, vcc, 0x80000, v206
	v_lshl_add_u64 v[96:97], v[206:207], 0, s[8:9]
	s_nop 0
	v_addc_co_u32_e32 v99, vcc, 0, v207, vcc
	s_mov_b64 s[8:9], 0x80200
	global_load_dwordx4 v[126:129], v[98:99], off
	global_load_dwordx4 v[122:125], v[96:97], off offset:16
	v_lshl_add_u64 v[96:97], v[206:207], 0, s[8:9]
	s_mov_b32 s8, 0x90000
	global_load_dwordx4 v[118:121], v[98:99], off offset:512
	global_load_dwordx4 v[114:117], v[96:97], off offset:16
	v_add_co_u32_e32 v98, vcc, s8, v206
	v_lshl_add_u64 v[96:97], v[206:207], 0, s[4:5]
	s_nop 0
	v_addc_co_u32_e32 v99, vcc, 0, v207, vcc
	s_mov_b64 s[8:9], 0x90200
	global_load_dwordx4 v[108:111], v[98:99], off
	global_load_dwordx4 v[104:107], v[96:97], off offset:16
	v_lshl_add_u64 v[96:97], v[206:207], 0, s[8:9]
	global_load_dwordx4 v[100:103], v[98:99], off offset:512
	s_nop 0
	global_load_dwordx4 v[96:99], v[96:97], off offset:16
	v_add_u32_e32 v162, 32, v204
	v_ashrrev_i32_e32 v163, 31, v162
	v_lshlrev_b64 v[164:165], 12, v[162:163]
	v_lshl_add_u64 v[164:165], s[78:79], 0, v[164:165]
	v_lshl_add_u64 v[164:165], v[202:203], 2, v[164:165]
	s_waitcnt vmcnt(24)
	v_pk_add_f32 v[94:95], v[94:95], v[160:161]
	v_pk_add_f32 v[92:93], v[92:93], v[158:159]
	v_pk_add_f32 v[88:89], v[88:89], v[154:155]
	v_pk_add_f32 v[90:91], v[90:91], v[156:157]
	global_store_dwordx4 v[164:165], v[92:95], off
	global_store_dwordx4 v[164:165], v[88:91], off offset:16
	v_cvt_pk_bf16_f32 v154, v92, v93
	v_cvt_pk_bf16_f32 v155, v94, v95
	v_cvt_pk_bf16_f32 v156, v88, v89
	v_lshlrev_b64 v[166:167], 11, v[162:163]
	v_mul_f32_e32 v93, v93, v93
	v_mul_f32_e32 v89, v89, v89
	v_fmac_f32_e32 v93, v92, v92
	v_mul_f32_e32 v92, v95, v95
	v_fmac_f32_e32 v89, v88, v88
	v_mul_f32_e32 v88, v91, v91
	v_lshl_add_u64 v[166:167], s[6:7], 0, v[166:167]
	v_fmac_f32_e32 v92, v94, v94
	v_fmac_f32_e32 v88, v90, v90
	v_lshl_add_u64 v[166:167], v[202:203], 1, v[166:167]
	v_add_f32_e32 v92, v93, v92
	v_add_f32_e32 v88, v89, v88
	v_pk_add_f32 v[86:87], v[86:87], v[152:153]
	v_pk_add_f32 v[84:85], v[84:85], v[150:151]
	v_pk_add_f32 v[80:81], v[80:81], v[146:147]
	v_cvt_pk_bf16_f32 v157, v90, v91
	global_store_dwordx4 v[166:167], v[154:157], off
	v_add_f32_e32 v92, v92, v88
	v_pk_add_f32 v[82:83], v[82:83], v[148:149]
	global_store_dwordx4 v[164:165], v[84:87], off offset:512
	global_store_dwordx4 v[164:165], v[80:83], off offset:528
	v_cvt_pk_bf16_f32 v88, v84, v85
	v_cvt_pk_bf16_f32 v89, v86, v87
	v_cvt_pk_bf16_f32 v90, v80, v81
	v_cvt_pk_bf16_f32 v91, v82, v83
	s_nop 0
	v_mul_f32_e32 v85, v85, v85
	v_mul_f32_e32 v81, v81, v81
	v_fmac_f32_e32 v85, v84, v84
	v_mul_f32_e32 v84, v87, v87
	v_fmac_f32_e32 v81, v80, v80
	v_mul_f32_e32 v80, v83, v83
	v_fmac_f32_e32 v84, v86, v86
	v_fmac_f32_e32 v80, v82, v82
	v_add_f32_e32 v84, v85, v84
	v_add_f32_e32 v80, v81, v80
	v_add_f32_e32 v80, v84, v80
	v_add_f32_e32 v80, v92, v80
	v_mov_b32_e32 v81, v80
	s_nop 1
	v_permlane16_swap_b32_e32 v80, v81
	v_add_f32_e32 v80, v80, v81
	v_mov_b32_e32 v81, v80
	s_nop 1
	v_permlane32_swap_b32_e32 v80, v81
	global_store_dwordx4 v[166:167], v[88:91], off offset:256
	s_and_saveexec_b64 s[88:89], s[40:41]
	v_readlane_b32 s13, v255, 49
	s_cbranch_execz .LBB0_239
	v_lshlrev_b64 v[82:83], 6, v[162:163]
	v_lshl_add_u64 v[82:83], s[96:97], 0, v[82:83]
	v_lshl_add_u64 v[82:83], s[86:87], 2, v[82:83]
	s_lshl_b32 s46, s35, 2
	v_lshl_add_u64 v[82:83], v[82:83], 0, s[46:47]
	v_add_f32_e32 v80, v80, v81
	global_store_dword v[82:83], v80, off
.LBB0_239:
	s_or_b64 exec, exec, s[88:89]
	v_add_u32_e32 v80, 48, v204
	v_ashrrev_i32_e32 v81, 31, v80
	v_lshlrev_b64 v[82:83], 12, v[80:81]
	v_lshl_add_u64 v[82:83], s[78:79], 0, v[82:83]
	v_lshl_add_u64 v[86:87], v[202:203], 2, v[82:83]
	v_lshlrev_b64 v[82:83], 11, v[80:81]
	v_lshl_add_u64 v[82:83], s[6:7], 0, v[82:83]
	s_waitcnt vmcnt(26)
	v_pk_add_f32 v[78:79], v[78:79], v[144:145]
	v_pk_add_f32 v[76:77], v[76:77], v[142:143]
	v_pk_add_f32 v[72:73], v[72:73], v[138:139]
	v_lshl_add_u64 v[88:89], v[202:203], 1, v[82:83]
	v_pk_add_f32 v[74:75], v[74:75], v[140:141]
	global_store_dwordx4 v[86:87], v[76:79], off
	global_store_dwordx4 v[86:87], v[72:75], off offset:16
	v_cvt_pk_bf16_f32 v82, v76, v77
	v_cvt_pk_bf16_f32 v83, v78, v79
	v_cvt_pk_bf16_f32 v84, v72, v73
	v_pk_add_f32 v[70:71], v[70:71], v[132:133]
	v_mul_f32_e32 v77, v77, v77
	v_mul_f32_e32 v73, v73, v73
	v_fmac_f32_e32 v77, v76, v76
	v_mul_f32_e32 v76, v79, v79
	v_fmac_f32_e32 v73, v72, v72
	v_mul_f32_e32 v72, v75, v75
	v_fmac_f32_e32 v76, v78, v78
	v_fmac_f32_e32 v72, v74, v74
	v_add_f32_e32 v76, v77, v76
	v_add_f32_e32 v72, v73, v72
	v_pk_add_f32 v[68:69], v[68:69], v[130:131]
	v_pk_add_f32 v[64:65], v[64:65], v[134:135]
	v_cvt_pk_bf16_f32 v85, v74, v75
	global_store_dwordx4 v[88:89], v[82:85], off
	v_add_f32_e32 v76, v76, v72
	v_pk_add_f32 v[66:67], v[66:67], v[136:137]
	global_store_dwordx4 v[86:87], v[68:71], off offset:512
	global_store_dwordx4 v[86:87], v[64:67], off offset:528
	v_cvt_pk_bf16_f32 v72, v68, v69
	v_cvt_pk_bf16_f32 v73, v70, v71
	v_cvt_pk_bf16_f32 v74, v64, v65
	v_cvt_pk_bf16_f32 v75, v66, v67
	s_nop 0
	v_mul_f32_e32 v69, v69, v69
	v_mul_f32_e32 v65, v65, v65
	v_fmac_f32_e32 v69, v68, v68
	v_mul_f32_e32 v68, v71, v71
	v_fmac_f32_e32 v65, v64, v64
	v_mul_f32_e32 v64, v67, v67
	v_fmac_f32_e32 v68, v70, v70
	v_fmac_f32_e32 v64, v66, v66
	v_add_f32_e32 v68, v69, v68
	v_add_f32_e32 v64, v65, v64
	v_add_f32_e32 v64, v68, v64
	v_add_f32_e32 v64, v76, v64
	v_mov_b32_e32 v65, v64
	s_nop 1
	v_permlane16_swap_b32_e32 v64, v65
	v_add_f32_e32 v64, v64, v65
	v_mov_b32_e32 v65, v64
	s_nop 1
	v_permlane32_swap_b32_e32 v64, v65
	global_store_dwordx4 v[88:89], v[72:75], off offset:256
	s_and_saveexec_b64 s[88:89], s[40:41]
	s_cbranch_execz .LBB0_241
	v_lshlrev_b64 v[66:67], 6, v[80:81]
	v_lshl_add_u64 v[66:67], s[96:97], 0, v[66:67]
	v_lshl_add_u64 v[66:67], s[86:87], 2, v[66:67]
	s_lshl_b32 s46, s35, 2
	v_lshl_add_u64 v[66:67], v[66:67], 0, s[46:47]
	v_add_f32_e32 v64, v64, v65
	global_store_dword v[66:67], v64, off
